# kmax per-row sum of squares: two ds_swizzle SWAP1/2 + lgkm waits replaced by DPP quad_perm adds
# baseline (speedup 1.0000x reference)
.LBB0_564:
	v_and_b32_e32 v29, 0xffff0000, v4
	v_and_b32_e32 v28, 0xffff0000, v8
	v_lshlrev_b32_e32 v27, 16, v4
	v_lshlrev_b32_e32 v26, 16, v8
	v_pk_mul_f32 v[28:29], v[28:29], v[28:29]
	v_and_b32_e32 v4, 0xffff0000, v9
	v_pk_fma_f32 v[26:27], v[26:27], v[26:27], v[28:29]
	v_lshlrev_b32_e32 v29, 16, v5
	v_and_b32_e32 v5, 0xffff0000, v5
	v_lshlrev_b32_e32 v28, 16, v9
	v_pk_mul_f32 v[4:5], v[4:5], v[4:5]
	v_and_b32_e32 v8, 0xffff0000, v10
	v_pk_fma_f32 v[4:5], v[28:29], v[28:29], v[4:5]
	v_mul_f32_e32 v29, v8, v8
	v_pk_add_f32 v[4:5], v[4:5], v[4:5] op_sel_hi:[0,1]
	v_lshlrev_b32_e32 v4, 16, v10
	v_lshlrev_b32_e32 v30, 16, v6
	v_lshlrev_b32_e32 v8, 16, v11
	v_pk_add_f32 v[26:27], v[26:27], v[26:27] op_sel_hi:[0,1]
	v_mul_f32_e32 v9, v4, v4
	v_and_b32_e32 v31, 0xffff0000, v6
	v_mul_f32_e32 v4, v30, v30
	v_lshlrev_b32_e32 v6, 16, v7
	v_mov_b32_e32 v28, v8
	v_pk_fma_f32 v[30:31], v[30:31], v[30:31], v[4:5] op_sel_hi:[1,1,0]
	v_and_b32_e32 v4, 0xffff0000, v11
	v_and_b32_e32 v7, 0xffff0000, v7
	v_mul_f32_e32 v26, v6, v6
	v_mul_f32_e32 v6, v8, v8
	v_pk_add_f32 v[8:9], v[8:9], v[28:29]
	v_mul_f32_e32 v30, v4, v4
	v_mul_f32_e32 v4, v7, v7
	v_mov_b32_e32 v7, v9
	v_pk_add_f32 v[6:7], v[6:7], v[30:31]
	v_pk_add_f32 v[4:5], v[26:27], v[4:5]
	v_lshl_add_u64 v[2:3], v[2:3], 0, s[0:1]
	v_pk_add_f32 v[4:5], v[6:7], v[4:5]
	s_and_b64 vcc, exec, s[2:3]
	v_add_f32_e32 v4, v4, v5
	s_waitcnt lgkmcnt(0)
	s_nop 1
	v_add_f32_dpp v4, v4, v4 quad_perm:[1,0,3,2] row_mask:0xf bank_mask:0xf
	s_nop 1
	v_add_f32_dpp v4, v4, v4 quad_perm:[2,3,0,1] row_mask:0xf bank_mask:0xf
	v_max_f32_e32 v5, v24, v24
	v_max_f32_e32 v24, v5, v4
	s_cbranch_vccnz .LBB0_396
	s_waitcnt vmcnt(0)
	v_mov_b64_e32 v[8:9], v[16:17]
	v_mov_b64_e32 v[4:5], v[12:13]
	s_mov_b32 s10, s8
	v_mov_b64_e32 v[10:11], v[18:19]
	v_mov_b64_e32 v[6:7], v[14:15]
	s_ashr_i32 s8, s9, 13
	s_cmp_eq_u32 s8, s10
	s_cbranch_scc1 .LBB0_561
	s_branch .LBB0_558
